# weight-conversion loads: fetch both 32-row halves of a 64x64 tile concurrently (early touch of the second half); rstd-table loads issued together; scan LDS reads issued together
# speedup vs baseline: 1.0163x; 1.0140x over previous
.LBB0_150:
	ds_read_b128 v[110:113], v108
	ds_read_b128 v[114:117], v108 offset:64
	s_mov_b32 s5, s4
	s_add_i32 s4, s4, 8
	s_mov_b32 s6, 0xfff20000
	s_mov_b32 s7, 0xfff40000
	s_waitcnt lgkmcnt(1)
	v_mfma_f32_16x16x32_bf16 v[16:19], v[16:19], v[110:113], v[96:99]
	s_waitcnt lgkmcnt(0)
	v_mfma_f32_16x16x32_bf16 v[8:11], v[8:11], v[114:117], v[16:19]
	s_nop 7
	v_cvt_pk_bf16_f32 v8, v8, v9
	v_cvt_pk_bf16_f32 v9, v10, v11
	v_add_co_u32_e32 v10, vcc, s6, v106
	s_min_u32 s6, s4, 0xf7
	s_lshl_b32 s6, s6, 12
	s_add_i32 s6, s6, s8
	v_addc_co_u32_e32 v11, vcc, -1, v107, vcc
	s_lshl_b32 s72, s6, 1
	ds_write_b64 v0, v[8:9] offset:2304
	global_store_dwordx2 v[10:11], v[8:9], off
	v_lshl_add_u64 v[8:9], v[104:105], 0, s[72:73]
	v_lshl_add_u64 v[96:97], v[2:3], 0, s[72:73]
	global_load_dwordx4 v[16:19], v[8:9], off
	s_nop 0
	global_load_dwordx4 v[8:11], v[8:9], off offset:1024
	s_add_i32 s6, s5, 9
	global_load_dwordx2 v[98:99], v[96:97], off
	s_waitcnt lgkmcnt(0)
	s_barrier
	ds_read_b128 v[110:113], v108 offset:2304
	ds_read_b128 v[114:117], v108 offset:2368
	s_waitcnt lgkmcnt(1)
	v_mfma_f32_16x16x32_bf16 v[20:23], v[20:23], v[110:113], v[88:91]
	s_min_u32 s6, s6, 0xf7
	s_lshl_b32 s6, s6, 12
	s_waitcnt lgkmcnt(0)
	v_mfma_f32_16x16x32_bf16 v[12:15], v[12:15], v[114:117], v[20:23]
	s_add_i32 s6, s6, s8
	s_lshl_b32 s72, s6, 1
	v_lshl_add_u64 v[88:89], v[2:3], 0, s[72:73]
	s_nop 4
	v_cvt_pk_bf16_f32 v12, v12, v13
	v_cvt_pk_bf16_f32 v13, v14, v15
	v_add_co_u32_e32 v14, vcc, s7, v106
	ds_write_b64 v0, v[12:13]
	s_nop 0
	v_addc_co_u32_e32 v15, vcc, -1, v107, vcc
	global_store_dwordx2 v[14:15], v[12:13], off
	v_lshl_add_u64 v[12:13], v[104:105], 0, s[72:73]
	global_load_dwordx4 v[20:23], v[12:13], off
	s_nop 0
	global_load_dwordx4 v[12:15], v[12:13], off offset:1024
	s_add_i32 s6, s5, 10
	global_load_dwordx2 v[90:91], v[88:89], off
	s_waitcnt lgkmcnt(0)
	s_barrier
	ds_read_b128 v[110:113], v108
	ds_read_b128 v[114:117], v108 offset:64
	s_waitcnt lgkmcnt(1)
	v_mfma_f32_16x16x32_bf16 v[28:31], v[28:31], v[110:113], v[84:87]
	s_min_u32 s6, s6, 0xf7
	s_mov_b32 s7, 0xfff60000
	s_waitcnt lgkmcnt(0)
	v_mfma_f32_16x16x32_bf16 v[24:27], v[24:27], v[114:117], v[28:31]
	s_lshl_b32 s6, s6, 12
	s_add_i32 s6, s6, s8
	s_lshl_b32 s72, s6, 1
	s_nop 4
	v_cvt_pk_bf16_f32 v24, v24, v25
	v_cvt_pk_bf16_f32 v25, v26, v27
	v_add_co_u32_e32 v26, vcc, s7, v106
	ds_write_b64 v0, v[24:25] offset:2304
	s_nop 0
	v_addc_co_u32_e32 v27, vcc, -1, v107, vcc
	global_store_dwordx2 v[26:27], v[24:25], off
	v_lshl_add_u64 v[24:25], v[104:105], 0, s[72:73]
	v_lshl_add_u64 v[84:85], v[2:3], 0, s[72:73]
	global_load_dwordx4 v[28:31], v[24:25], off
	s_nop 0
	global_load_dwordx4 v[24:27], v[24:25], off offset:1024
	s_add_i32 s6, s5, 11
	global_load_dwordx2 v[86:87], v[84:85], off
	s_waitcnt lgkmcnt(0)
	s_barrier
	ds_read_b128 v[110:113], v108 offset:2304
	ds_read_b128 v[114:117], v108 offset:2368
	s_waitcnt lgkmcnt(1)
	v_mfma_f32_16x16x32_bf16 v[36:39], v[36:39], v[110:113], v[80:83]
	s_min_u32 s6, s6, 0xf7
	s_mov_b32 s7, 0xfff80000
	s_waitcnt lgkmcnt(0)
	v_mfma_f32_16x16x32_bf16 v[32:35], v[32:35], v[114:117], v[36:39]
	s_lshl_b32 s6, s6, 12
	s_add_i32 s6, s6, s8
	s_lshl_b32 s72, s6, 1
	s_nop 4
	v_cvt_pk_bf16_f32 v32, v32, v33
	v_cvt_pk_bf16_f32 v33, v34, v35
	v_add_co_u32_e32 v34, vcc, s7, v106
	ds_write_b64 v0, v[32:33]
	s_nop 0
	v_addc_co_u32_e32 v35, vcc, -1, v107, vcc
	global_store_dwordx2 v[34:35], v[32:33], off
	v_lshl_add_u64 v[32:33], v[104:105], 0, s[72:73]
	v_lshl_add_u64 v[80:81], v[2:3], 0, s[72:73]
	global_load_dwordx4 v[36:39], v[32:33], off
	s_nop 0
	global_load_dwordx4 v[32:35], v[32:33], off offset:1024
	s_add_i32 s6, s5, 12
	global_load_dwordx2 v[82:83], v[80:81], off
	s_waitcnt lgkmcnt(0)
	s_barrier
	ds_read_b128 v[110:113], v108
	ds_read_b128 v[114:117], v108 offset:64
	s_waitcnt lgkmcnt(1)
	v_mfma_f32_16x16x32_bf16 v[44:47], v[44:47], v[110:113], v[76:79]
	s_min_u32 s6, s6, 0xf7
	s_mov_b32 s7, 0xfffa0000
	s_waitcnt lgkmcnt(0)
	v_mfma_f32_16x16x32_bf16 v[40:43], v[40:43], v[114:117], v[44:47]
	s_lshl_b32 s6, s6, 12
	s_add_i32 s6, s6, s8
	s_lshl_b32 s72, s6, 1
	s_nop 4
	v_cvt_pk_bf16_f32 v40, v40, v41
	v_cvt_pk_bf16_f32 v41, v42, v43
	v_add_co_u32_e32 v42, vcc, s7, v106
	ds_write_b64 v0, v[40:41] offset:2304
	s_nop 0
	v_addc_co_u32_e32 v43, vcc, -1, v107, vcc
	global_store_dwordx2 v[42:43], v[40:41], off
	v_lshl_add_u64 v[40:41], v[104:105], 0, s[72:73]
	v_lshl_add_u64 v[76:77], v[2:3], 0, s[72:73]
	global_load_dwordx4 v[44:47], v[40:41], off
	s_nop 0
	global_load_dwordx4 v[40:43], v[40:41], off offset:1024
	s_add_i32 s6, s5, 13
	global_load_dwordx2 v[78:79], v[76:77], off
	s_waitcnt lgkmcnt(0)
	s_barrier
	ds_read_b128 v[110:113], v108 offset:2304
	ds_read_b128 v[114:117], v108 offset:2368
	s_waitcnt lgkmcnt(1)
	v_mfma_f32_16x16x32_bf16 v[52:55], v[52:55], v[110:113], v[72:75]
	s_min_u32 s6, s6, 0xf7
	s_mov_b32 s7, 0xfffc0000
	s_waitcnt lgkmcnt(0)
	v_mfma_f32_16x16x32_bf16 v[48:51], v[48:51], v[114:117], v[52:55]
	s_lshl_b32 s6, s6, 12
	s_add_i32 s6, s6, s8
	s_lshl_b32 s72, s6, 1
	s_nop 4
	v_cvt_pk_bf16_f32 v48, v48, v49
	v_cvt_pk_bf16_f32 v49, v50, v51
	v_add_co_u32_e32 v50, vcc, s7, v106
	ds_write_b64 v0, v[48:49]
	s_nop 0
	v_addc_co_u32_e32 v51, vcc, -1, v107, vcc
	global_store_dwordx2 v[50:51], v[48:49], off
	v_lshl_add_u64 v[48:49], v[104:105], 0, s[72:73]
	v_lshl_add_u64 v[72:73], v[2:3], 0, s[72:73]
	global_load_dwordx4 v[52:55], v[48:49], off
	s_nop 0
	global_load_dwordx4 v[48:51], v[48:49], off offset:1024
	s_add_i32 s6, s5, 14
	global_load_dwordx2 v[74:75], v[72:73], off
	s_waitcnt lgkmcnt(0)
	s_barrier
	ds_read_b128 v[110:113], v108
	ds_read_b128 v[114:117], v108 offset:64
	s_waitcnt lgkmcnt(1)
	v_mfma_f32_16x16x32_bf16 v[60:63], v[60:63], v[110:113], v[92:95]
	s_min_u32 s6, s6, 0xf7
	s_mov_b32 s7, 0xfffe0000
	s_waitcnt lgkmcnt(0)
	v_mfma_f32_16x16x32_bf16 v[56:59], v[56:59], v[114:117], v[60:63]
	s_lshl_b32 s6, s6, 12
	s_add_i32 s6, s6, s8
	s_lshl_b32 s72, s6, 1
	s_nop 4
	v_cvt_pk_bf16_f32 v56, v56, v57
	v_cvt_pk_bf16_f32 v57, v58, v59
	v_add_co_u32_e32 v58, vcc, s7, v106
	ds_write_b64 v0, v[56:57] offset:2304
	s_nop 0
	v_addc_co_u32_e32 v59, vcc, -1, v107, vcc
	global_store_dwordx2 v[58:59], v[56:57], off
	v_lshl_add_u64 v[56:57], v[104:105], 0, s[72:73]
	v_lshl_add_u64 v[72:73], v[2:3], 0, s[72:73]
	global_load_dwordx4 v[60:63], v[56:57], off
	s_nop 0
	global_load_dwordx4 v[56:59], v[56:57], off offset:1024
	s_add_i32 s5, s5, 15
	global_load_dwordx2 v[94:95], v[72:73], off
	s_waitcnt lgkmcnt(0)
	s_barrier
	ds_read_b128 v[110:113], v108 offset:2304
	ds_read_b128 v[114:117], v108 offset:2368
	s_waitcnt vmcnt(29) lgkmcnt(1)
	v_mfma_f32_16x16x32_bf16 v[68:71], v[68:71], v[110:113], v[100:103]
	s_cmpk_gt_u32 s5, 0xfe
	s_waitcnt vmcnt(28) lgkmcnt(0)
	v_mfma_f32_16x16x32_bf16 v[64:67], v[64:67], v[114:117], v[68:71]
	s_nop 7
	v_cvt_pk_bf16_f32 v64, v64, v65
	v_cvt_pk_bf16_f32 v65, v66, v67
	ds_write_b64 v0, v[64:65]
	s_cbranch_scc1 .LBB0_149
	global_store_dwordx2 v[106:107], v[64:65], off
	s_branch .LBB0_149

.LBB0_211:
	s_add_i32 s34, s70, 63
	s_lshr_b32 s79, s34, 6
	s_add_i32 s34, s37, 63
	s_ashr_i32 s66, s34, 6
	s_mul_i32 s34, s11, 37
	s_add_i32 s34, s10, s34
	s_ashr_i32 s67, s34, 31
	s_abs_i32 s34, s34
	v_readlane_b32 s35, v251, 63
	s_mul_hi_u32 s35, s34, s35
	v_readlane_b32 s40, v251, 62
	s_mul_i32 s35, s35, s40
	s_sub_i32 s34, s34, s35
	s_sub_i32 s35, s34, s40
	s_cmp_ge_u32 s34, s40
	s_cselect_b32 s34, s35, s34
	s_sub_i32 s35, s34, s40
	s_cmp_ge_u32 s34, s40
	s_cselect_b32 s34, s35, s34
	s_xor_b32 s68, s34, s67
	s_sub_i32 s82, s68, s67
	s_mul_i32 s79, s79, s66
	s_cmp_lg_u64 s[6:7], 0
	s_cselect_b64 s[34:35], -1, 0
	s_cmp_lt_i32 s82, s79
	s_cselect_b64 s[40:41], -1, 0
	s_and_b64 vcc, exec, s[40:41]
	s_cbranch_vccz .LBB0_233
	s_abs_i32 s42, s66
	v_cvt_f32_u32_e32 v0, s42
	s_sub_i32 s45, 0, s42
	s_abs_i32 s44, s82
	s_xor_b32 s43, s82, s66
	v_rcp_iflag_f32_e32 v0, v0
	s_ashr_i32 s43, s43, 31
	v_mov_b32_e32 v2, v202
	v_mul_f32_e32 v0, 0x4f7ffffe, v0
	v_cvt_u32_f32_e32 v0, v0
	s_waitcnt lgkmcnt(0)
	v_ashrrev_i32_e32 v3, 4, v2
	v_mov_b32_e32 v46, 1.0
	v_readfirstlane_b32 s64, v0
	s_mul_i32 s45, s45, s64
	s_mul_hi_u32 s45, s64, s45
	s_add_i32 s64, s64, s45
	s_mul_hi_u32 s45, s44, s64
	s_mul_i32 s64, s45, s42
	s_sub_i32 s44, s44, s64
	s_add_i32 s65, s45, 1
	s_sub_i32 s64, s44, s42
	s_cmp_ge_u32 s44, s42
	s_cselect_b32 s45, s65, s45
	s_cselect_b32 s44, s64, s44
	s_add_i32 s64, s45, 1
	s_cmp_ge_u32 s44, s42
	s_cselect_b32 s42, s64, s45
	s_xor_b32 s42, s42, s43
	s_sub_i32 s43, s42, s43
	s_mul_i32 s42, s43, s66
	s_sub_i32 s42, s82, s42
	v_lshlrev_b32_e32 v0, 2, v2
	v_lshl_add_u32 v56, s43, 6, v3
	v_mov_b32_e32 v2, v1
	v_mov_b32_e32 v3, v1
	s_lshl_b32 s42, s42, 6
	v_and_b32_e32 v41, 60, v0
	v_mov_b32_e32 v0, v1
	v_mov_b64_e32 v[22:23], v[2:3]
	v_or_b32_e32 v43, s42, v41
	s_ashr_i32 s43, s42, 31
	v_cmp_gt_i32_e32 vcc, s70, v56
	v_mov_b64_e32 v[20:21], v[0:1]
	s_and_saveexec_b64 s[44:45], vcc
	s_cbranch_execz .LBB0_222
	v_mov_b32_e32 v2, v1
	v_mov_b32_e32 v3, v1
	v_mov_b32_e32 v0, v1
	v_mov_b64_e32 v[22:23], v[2:3]
	v_cmp_gt_i32_e32 vcc, s37, v43
	v_mov_b64_e32 v[20:21], v[0:1]
	s_and_saveexec_b64 s[64:65], vcc
	s_cbranch_execz .LBB0_215
	v_mad_i64_i32 v[2:3], s[84:85], v56, s37, 0
	v_lshl_add_u64 v[2:3], v[2:3], 2, s[0:1]
	v_lshl_add_u64 v[2:3], s[42:43], 2, v[2:3]
	v_lshlrev_b32_e32 v0, 2, v41
	v_lshl_add_u64 v[2:3], v[2:3], 0, v[0:1]
	global_load_dwordx4 v[20:23], v[2:3], off
	s_cmp_lt_i32 s70, 64
	s_cbranch_scc1 .Lcpf_skip0
	s_lshl_b32 s100, s37, 7
	s_mov_b32 s101, 0
	v_lshl_add_u64 v[70:71], s[100:101], 0, v[2:3]
	global_load_dwordx4 v[66:69], v[70:71], off
.Lcpf_skip0:
.LBB0_215:
	s_or_b64 exec, exec, s[64:65]
	s_andn2_b64 vcc, exec, s[34:35]
	s_cbranch_vccnz .LBB0_470
	v_ashrrev_i32_e32 v57, 31, v56
	v_lshl_add_u64 v[2:3], v[56:57], 2, s[6:7]
	global_load_dword v0, v[2:3], off
	s_cmp_gt_i32 s39, 1
	s_mov_b64 s[64:65], -1
	s_cbranch_scc0 .LBB0_218

.LBB0_233:
	v_readlane_b32 s42, v251, 60
	s_add_i32 s69, s82, s42
	s_cmp_ge_i32 s69, s79
	s_cbranch_scc1 .LBB0_255
	s_abs_i32 s42, s66
	s_waitcnt vmcnt(0)
	v_cvt_f32_u32_e32 v0, s42
	s_sub_i32 s45, 0, s42
	s_abs_i32 s44, s69
	s_xor_b32 s43, s69, s66
	v_rcp_iflag_f32_e32 v0, v0
	s_ashr_i32 s43, s43, 31
	v_mov_b32_e32 v2, v202
	v_mul_f32_e32 v0, 0x4f7ffffe, v0
	v_cvt_u32_f32_e32 v0, v0
	s_waitcnt lgkmcnt(0)
	v_ashrrev_i32_e32 v3, 4, v2
	v_mov_b32_e32 v44, 1.0
	v_readfirstlane_b32 s64, v0
	s_mul_i32 s45, s45, s64
	s_mul_hi_u32 s45, s64, s45
	s_add_i32 s64, s64, s45
	s_mul_hi_u32 s45, s44, s64
	s_mul_i32 s64, s45, s42
	s_sub_i32 s44, s44, s64
	s_add_i32 s65, s45, 1
	s_sub_i32 s64, s44, s42
	s_cmp_ge_u32 s44, s42
	s_cselect_b32 s45, s65, s45
	s_cselect_b32 s44, s64, s44
	s_add_i32 s64, s45, 1
	s_cmp_ge_u32 s44, s42
	s_cselect_b32 s42, s64, s45
	s_xor_b32 s42, s42, s43
	s_sub_i32 s43, s42, s43
	s_mul_i32 s42, s43, s66
	s_sub_i32 s42, s69, s42
	v_lshlrev_b32_e32 v0, 2, v2
	v_lshl_add_u32 v56, s43, 6, v3
	v_mov_b32_e32 v2, v1
	v_mov_b32_e32 v3, v1
	s_lshl_b32 s42, s42, 6
	v_and_b32_e32 v41, 60, v0
	v_mov_b32_e32 v0, v1
	v_mov_b64_e32 v[18:19], v[2:3]
	v_or_b32_e32 v43, s42, v41
	s_ashr_i32 s43, s42, 31
	v_cmp_gt_i32_e32 vcc, s70, v56
	v_mov_b64_e32 v[16:17], v[0:1]
	s_and_saveexec_b64 s[44:45], vcc
	s_cbranch_execz .LBB0_244
	v_mov_b32_e32 v2, v1
	v_mov_b32_e32 v3, v1
	v_mov_b32_e32 v0, v1
	v_mov_b64_e32 v[18:19], v[2:3]
	v_cmp_gt_i32_e32 vcc, s37, v43
	v_mov_b64_e32 v[16:17], v[0:1]
	s_and_saveexec_b64 s[64:65], vcc
	s_cbranch_execz .LBB0_237
	v_mad_i64_i32 v[2:3], s[84:85], v56, s37, 0
	v_lshl_add_u64 v[2:3], v[2:3], 2, s[0:1]
	v_lshl_add_u64 v[2:3], s[42:43], 2, v[2:3]
	v_lshlrev_b32_e32 v0, 2, v41
	v_lshl_add_u64 v[2:3], v[2:3], 0, v[0:1]
	global_load_dwordx4 v[16:19], v[2:3], off
	s_cmp_lt_i32 s70, 64
	s_cbranch_scc1 .Lcpf_skip1
	s_lshl_b32 s100, s37, 7
	s_mov_b32 s101, 0
	v_lshl_add_u64 v[70:71], s[100:101], 0, v[2:3]
	global_load_dwordx4 v[66:69], v[70:71], off

.LBB0_255:
	v_readlane_b32 s42, v251, 60
	s_add_i32 s69, s69, s42
	s_cmp_ge_i32 s69, s79
	s_cbranch_scc1 .LBB0_277
	s_abs_i32 s42, s66
	s_waitcnt vmcnt(0)
	v_cvt_f32_u32_e32 v0, s42
	s_sub_i32 s45, 0, s42
	s_abs_i32 s44, s69
	s_xor_b32 s43, s69, s66
	v_rcp_iflag_f32_e32 v0, v0
	s_ashr_i32 s43, s43, 31
	v_mov_b32_e32 v2, v202
	v_mul_f32_e32 v0, 0x4f7ffffe, v0
	v_cvt_u32_f32_e32 v0, v0
	s_waitcnt lgkmcnt(0)
	v_ashrrev_i32_e32 v3, 4, v2
	v_mov_b32_e32 v40, 1.0
	v_readfirstlane_b32 s64, v0
	s_mul_i32 s45, s45, s64
	s_mul_hi_u32 s45, s64, s45
	s_add_i32 s64, s64, s45
	s_mul_hi_u32 s45, s44, s64
	s_mul_i32 s64, s45, s42
	s_sub_i32 s44, s44, s64
	s_add_i32 s65, s45, 1
	s_sub_i32 s64, s44, s42
	s_cmp_ge_u32 s44, s42
	s_cselect_b32 s45, s65, s45
	s_cselect_b32 s44, s64, s44
	s_add_i32 s64, s45, 1
	s_cmp_ge_u32 s44, s42
	s_cselect_b32 s42, s64, s45
	s_xor_b32 s42, s42, s43
	s_sub_i32 s43, s42, s43
	s_mul_i32 s42, s43, s66
	s_sub_i32 s42, s69, s42
	v_lshlrev_b32_e32 v0, 2, v2
	v_lshl_add_u32 v56, s43, 6, v3
	v_mov_b32_e32 v2, v1
	v_mov_b32_e32 v3, v1
	s_lshl_b32 s42, s42, 6
	v_and_b32_e32 v41, 60, v0
	v_mov_b32_e32 v0, v1
	v_mov_b64_e32 v[14:15], v[2:3]
	v_or_b32_e32 v43, s42, v41
	s_ashr_i32 s43, s42, 31
	v_cmp_gt_i32_e32 vcc, s70, v56
	v_mov_b64_e32 v[12:13], v[0:1]
	s_and_saveexec_b64 s[44:45], vcc
	s_cbranch_execz .LBB0_266
	v_mov_b32_e32 v2, v1
	v_mov_b32_e32 v3, v1
	v_mov_b32_e32 v0, v1
	v_mov_b64_e32 v[14:15], v[2:3]
	v_cmp_gt_i32_e32 vcc, s37, v43
	v_mov_b64_e32 v[12:13], v[0:1]
	s_and_saveexec_b64 s[64:65], vcc
	s_cbranch_execz .LBB0_259
	v_mad_i64_i32 v[2:3], s[84:85], v56, s37, 0
	v_lshl_add_u64 v[2:3], v[2:3], 2, s[0:1]
	v_lshl_add_u64 v[2:3], s[42:43], 2, v[2:3]
	v_lshlrev_b32_e32 v0, 2, v41
	v_lshl_add_u64 v[2:3], v[2:3], 0, v[0:1]
	global_load_dwordx4 v[12:15], v[2:3], off
	s_cmp_lt_i32 s70, 64
	s_cbranch_scc1 .Lcpf_skip2
	s_lshl_b32 s100, s37, 7
	s_mov_b32 s101, 0
	v_lshl_add_u64 v[70:71], s[100:101], 0, v[2:3]
	global_load_dwordx4 v[66:69], v[70:71], off

.LBB0_277:
	v_readlane_b32 s42, v251, 60
	s_add_i32 s69, s69, s42
	s_cmp_ge_i32 s69, s79
	s_cbranch_scc1 .LBB0_299
	s_abs_i32 s42, s66
	s_waitcnt vmcnt(0)
	v_cvt_f32_u32_e32 v0, s42
	s_sub_i32 s45, 0, s42
	s_abs_i32 s44, s69
	s_xor_b32 s43, s69, s66
	v_rcp_iflag_f32_e32 v0, v0
	s_ashr_i32 s43, s43, 31
	v_mov_b32_e32 v2, v202
	v_mul_f32_e32 v0, 0x4f7ffffe, v0
	v_cvt_u32_f32_e32 v0, v0
	s_waitcnt lgkmcnt(0)
	v_ashrrev_i32_e32 v3, 4, v2
	v_mov_b32_e32 v42, 1.0
	v_readfirstlane_b32 s64, v0
	s_mul_i32 s45, s45, s64
	s_mul_hi_u32 s45, s64, s45
	s_add_i32 s64, s64, s45
	s_mul_hi_u32 s45, s44, s64
	s_mul_i32 s64, s45, s42
	s_sub_i32 s44, s44, s64
	s_add_i32 s65, s45, 1
	s_sub_i32 s64, s44, s42
	s_cmp_ge_u32 s44, s42
	s_cselect_b32 s45, s65, s45
	s_cselect_b32 s44, s64, s44
	s_add_i32 s64, s45, 1
	s_cmp_ge_u32 s44, s42
	s_cselect_b32 s42, s64, s45
	s_xor_b32 s42, s42, s43
	s_sub_i32 s43, s42, s43
	s_mul_i32 s42, s43, s66
	s_sub_i32 s42, s69, s42
	v_lshlrev_b32_e32 v0, 2, v2
	v_lshl_add_u32 v56, s43, 6, v3
	v_mov_b32_e32 v2, v1
	v_mov_b32_e32 v3, v1
	s_lshl_b32 s42, s42, 6
	v_and_b32_e32 v41, 60, v0
	v_mov_b32_e32 v0, v1
	v_mov_b64_e32 v[10:11], v[2:3]
	v_or_b32_e32 v43, s42, v41
	s_ashr_i32 s43, s42, 31
	v_cmp_gt_i32_e32 vcc, s70, v56
	v_mov_b64_e32 v[8:9], v[0:1]
	s_and_saveexec_b64 s[44:45], vcc
	s_cbranch_execz .LBB0_288
	v_mov_b32_e32 v2, v1
	v_mov_b32_e32 v3, v1
	v_mov_b32_e32 v0, v1
	v_mov_b64_e32 v[10:11], v[2:3]
	v_cmp_gt_i32_e32 vcc, s37, v43
	v_mov_b64_e32 v[8:9], v[0:1]
	s_and_saveexec_b64 s[64:65], vcc
	s_cbranch_execz .LBB0_281
	v_mad_i64_i32 v[2:3], s[84:85], v56, s37, 0
	v_lshl_add_u64 v[2:3], v[2:3], 2, s[0:1]
	v_lshl_add_u64 v[2:3], s[42:43], 2, v[2:3]
	v_lshlrev_b32_e32 v0, 2, v41
	v_lshl_add_u64 v[2:3], v[2:3], 0, v[0:1]
	global_load_dwordx4 v[8:11], v[2:3], off
	s_cmp_lt_i32 s70, 64
	s_cbranch_scc1 .Lcpf_skip3
	s_lshl_b32 s100, s37, 7
	s_mov_b32 s101, 0
	v_lshl_add_u64 v[70:71], s[100:101], 0, v[2:3]
	global_load_dwordx4 v[66:69], v[70:71], off

.LBB0_314:
	s_or_b64 exec, exec, s[40:41]
	v_readlane_b32 s40, v251, 55
	s_add_i32 s89, s82, s40
	s_waitcnt lgkmcnt(0)
	s_barrier
	s_cmp_ge_i32 s89, s79
	s_cselect_b64 s[40:41], -1, 0
	s_and_b64 vcc, exec, s[40:41]
	s_cbranch_vccnz .LBB0_342
	s_abs_i32 s43, s89
	s_mul_hi_u32 s44, s43, s87
	s_mul_i32 s45, s44, s83
	s_ashr_i32 s42, s89, 31
	s_sub_i32 s43, s43, s45
	s_xor_b32 s42, s42, s84
	s_add_i32 s45, s44, 1
	s_sub_i32 s64, s43, s83
	s_cmp_ge_u32 s43, s83
	s_cselect_b32 s44, s45, s44
	s_cselect_b32 s43, s64, s43
	s_add_i32 s45, s44, 1
	s_cmp_ge_u32 s43, s83
	v_mov_b32_e32 v0, v202
	s_cselect_b32 s43, s45, s44
	s_xor_b32 s43, s43, s42
	s_sub_i32 s43, s43, s42
	v_ashrrev_i32_e32 v2, 4, v0
	v_lshlrev_b32_e32 v0, 2, v0
	s_mul_i32 s42, s88, s43
	v_readlane_b32 s44, v252, 10
	v_and_b32_e32 v41, 60, v0
	v_lshl_add_u32 v56, s43, 6, v2
	s_mul_i32 s43, s85, s43
	s_add_i32 s44, s44, s86
	v_subrev_u32_e32 v0, s43, v41
	v_mov_b32_e32 v2, v1
	v_mov_b32_e32 v3, v1
	s_add_i32 s42, s44, s42
	v_add_u32_e32 v43, s44, v0
	v_mov_b32_e32 v0, v1
	v_mov_b64_e32 v[22:23], v[2:3]
	s_ashr_i32 s43, s42, 31
	v_cmp_gt_i32_e32 vcc, s70, v56
	v_mov_b32_e32 v46, 1.0
	v_mov_b64_e32 v[20:21], v[0:1]
	s_and_saveexec_b64 s[44:45], vcc
	s_cbranch_execz .LBB0_328
	v_mov_b32_e32 v2, v1
	v_mov_b32_e32 v3, v1
	v_mov_b32_e32 v0, v1
	v_mov_b64_e32 v[22:23], v[2:3]
	v_cmp_gt_i32_e32 vcc, s37, v43
	v_mov_b64_e32 v[20:21], v[0:1]
	s_and_saveexec_b64 s[64:65], vcc
	s_cbranch_execz .LBB0_318
	v_mad_i64_i32 v[2:3], s[66:67], v56, s37, 0
	v_lshl_add_u64 v[2:3], v[2:3], 2, s[0:1]
	v_lshl_add_u64 v[2:3], s[42:43], 2, v[2:3]
	v_lshlrev_b32_e32 v0, 2, v41
	v_lshl_add_u64 v[2:3], v[2:3], 0, v[0:1]
	global_load_dwordx4 v[20:23], v[2:3], off
	s_cmp_lt_i32 s70, 64
	s_cbranch_scc1 .Lcpf_skip4
	s_lshl_b32 s100, s37, 7
	s_mov_b32 s101, 0
	v_lshl_add_u64 v[70:71], s[100:101], 0, v[2:3]
	global_load_dwordx4 v[66:69], v[70:71], off
.Lcpf_skip4:
.LBB0_318:
	s_or_b64 exec, exec, s[64:65]
	s_andn2_b64 vcc, exec, s[34:35]
	s_cbranch_vccnz .LBB0_323
	v_ashrrev_i32_e32 v57, 31, v56
	v_lshl_add_u64 v[2:3], v[56:57], 2, s[6:7]
	global_load_dword v0, v[2:3], off
	s_cmp_lt_i32 s39, 2
	s_mov_b64 s[64:65], -1
	s_cbranch_scc1 .LBB0_324

.LBB0_356:
	s_or_b64 exec, exec, s[42:43]
	s_waitcnt lgkmcnt(0)
	s_barrier
	v_readlane_b32 s42, v252, 17
	s_add_i32 s42, s42, s82
	s_cmp_ge_i32 s42, s79
	s_cbranch_scc1 .LBB0_384
	s_ashr_i32 s43, s42, 31
	s_abs_i32 s42, s42
	s_mul_hi_u32 s44, s42, s87
	s_mul_i32 s45, s44, s83
	s_sub_i32 s42, s42, s45
	s_xor_b32 s43, s43, s84
	s_add_i32 s45, s44, 1
	s_sub_i32 s64, s42, s83
	s_cmp_ge_u32 s42, s83
	s_cselect_b32 s44, s45, s44
	s_cselect_b32 s42, s64, s42
	s_add_i32 s45, s44, 1
	s_cmp_ge_u32 s42, s83
	v_mov_b32_e32 v0, v202
	s_cselect_b32 s42, s45, s44
	s_xor_b32 s42, s42, s43
	s_sub_i32 s43, s42, s43
	v_ashrrev_i32_e32 v2, 4, v0
	v_lshlrev_b32_e32 v0, 2, v0
	s_mul_i32 s42, s88, s43
	v_readlane_b32 s44, v252, 18
	v_and_b32_e32 v41, 60, v0
	v_lshl_add_u32 v56, s43, 6, v2
	s_mul_i32 s43, s85, s43
	s_add_i32 s44, s44, s86
	v_subrev_u32_e32 v0, s43, v41
	v_mov_b32_e32 v2, v1
	v_mov_b32_e32 v3, v1
	s_add_i32 s42, s44, s42
	v_add_u32_e32 v43, s44, v0
	v_mov_b32_e32 v0, v1
	v_mov_b64_e32 v[18:19], v[2:3]
	s_ashr_i32 s43, s42, 31
	v_cmp_gt_i32_e32 vcc, s70, v56
	v_mov_b32_e32 v44, 1.0
	v_mov_b64_e32 v[16:17], v[0:1]
	s_and_saveexec_b64 s[44:45], vcc
	s_cbranch_execz .LBB0_370
	v_mov_b32_e32 v2, v1
	v_mov_b32_e32 v3, v1
	v_mov_b32_e32 v0, v1
	v_mov_b64_e32 v[18:19], v[2:3]
	v_cmp_gt_i32_e32 vcc, s37, v43
	v_mov_b64_e32 v[16:17], v[0:1]
	s_and_saveexec_b64 s[64:65], vcc
	s_cbranch_execz .LBB0_360
	v_mad_i64_i32 v[2:3], s[66:67], v56, s37, 0
	v_lshl_add_u64 v[2:3], v[2:3], 2, s[0:1]
	v_lshl_add_u64 v[2:3], s[42:43], 2, v[2:3]
	v_lshlrev_b32_e32 v0, 2, v41
	v_lshl_add_u64 v[2:3], v[2:3], 0, v[0:1]
	global_load_dwordx4 v[16:19], v[2:3], off
	s_cmp_lt_i32 s70, 64
	s_cbranch_scc1 .Lcpf_skip5
	s_lshl_b32 s100, s37, 7
	s_mov_b32 s101, 0
	v_lshl_add_u64 v[70:71], s[100:101], 0, v[2:3]
	global_load_dwordx4 v[66:69], v[70:71], off

.LBB0_398:
	s_or_b64 exec, exec, s[42:43]
	s_waitcnt lgkmcnt(0)
	s_barrier
	v_readlane_b32 s42, v252, 14
	s_add_i32 s42, s42, s82
	s_cmp_ge_i32 s42, s79
	s_cbranch_scc1 .LBB0_426
	s_ashr_i32 s43, s42, 31
	s_abs_i32 s42, s42
	s_mul_hi_u32 s44, s42, s87
	s_mul_i32 s45, s44, s83
	s_sub_i32 s42, s42, s45
	s_xor_b32 s43, s43, s84
	s_add_i32 s45, s44, 1
	s_sub_i32 s64, s42, s83
	s_cmp_ge_u32 s42, s83
	s_cselect_b32 s44, s45, s44
	s_cselect_b32 s42, s64, s42
	s_add_i32 s45, s44, 1
	s_cmp_ge_u32 s42, s83
	v_mov_b32_e32 v0, v202
	s_cselect_b32 s42, s45, s44
	s_xor_b32 s42, s42, s43
	s_sub_i32 s43, s42, s43
	v_ashrrev_i32_e32 v2, 4, v0
	v_lshlrev_b32_e32 v0, 2, v0
	s_mul_i32 s42, s88, s43
	v_readlane_b32 s44, v252, 15
	v_and_b32_e32 v41, 60, v0
	v_lshl_add_u32 v56, s43, 6, v2
	s_mul_i32 s43, s85, s43
	s_add_i32 s44, s44, s86
	v_subrev_u32_e32 v0, s43, v41
	v_mov_b32_e32 v2, v1
	v_mov_b32_e32 v3, v1
	s_add_i32 s42, s44, s42
	v_add_u32_e32 v43, s44, v0
	v_mov_b32_e32 v0, v1
	v_mov_b64_e32 v[14:15], v[2:3]
	s_ashr_i32 s43, s42, 31
	v_cmp_gt_i32_e32 vcc, s70, v56
	v_mov_b32_e32 v40, 1.0
	v_mov_b64_e32 v[12:13], v[0:1]
	s_and_saveexec_b64 s[44:45], vcc
	s_cbranch_execz .LBB0_412
	v_mov_b32_e32 v2, v1
	v_mov_b32_e32 v3, v1
	v_mov_b32_e32 v0, v1
	v_mov_b64_e32 v[14:15], v[2:3]
	v_cmp_gt_i32_e32 vcc, s37, v43
	v_mov_b64_e32 v[12:13], v[0:1]
	s_and_saveexec_b64 s[64:65], vcc
	s_cbranch_execz .LBB0_402
	v_mad_i64_i32 v[2:3], s[66:67], v56, s37, 0
	v_lshl_add_u64 v[2:3], v[2:3], 2, s[0:1]
	v_lshl_add_u64 v[2:3], s[42:43], 2, v[2:3]
	v_lshlrev_b32_e32 v0, 2, v41
	v_lshl_add_u64 v[2:3], v[2:3], 0, v[0:1]
	global_load_dwordx4 v[12:15], v[2:3], off
	s_cmp_lt_i32 s70, 64
	s_cbranch_scc1 .Lcpf_skip6
	s_lshl_b32 s100, s37, 7
	s_mov_b32 s101, 0
	v_lshl_add_u64 v[70:71], s[100:101], 0, v[2:3]
	global_load_dwordx4 v[66:69], v[70:71], off

.LBB0_440:
	s_or_b64 exec, exec, s[42:43]
	s_waitcnt lgkmcnt(0)
	s_barrier
	v_readlane_b32 s42, v252, 11
	s_add_i32 s42, s42, s82
	s_cmp_ge_i32 s42, s79
	s_cbranch_scc1 .LBB0_468
	s_ashr_i32 s43, s42, 31
	s_abs_i32 s42, s42
	s_mul_hi_u32 s44, s42, s87
	s_mul_i32 s45, s44, s83
	s_sub_i32 s42, s42, s45
	s_xor_b32 s43, s43, s84
	s_add_i32 s45, s44, 1
	s_sub_i32 s64, s42, s83
	s_cmp_ge_u32 s42, s83
	s_cselect_b32 s44, s45, s44
	s_cselect_b32 s42, s64, s42
	s_add_i32 s45, s44, 1
	s_cmp_ge_u32 s42, s83
	v_mov_b32_e32 v0, v202
	s_cselect_b32 s42, s45, s44
	s_xor_b32 s42, s42, s43
	s_sub_i32 s43, s42, s43
	v_ashrrev_i32_e32 v2, 4, v0
	v_lshlrev_b32_e32 v0, 2, v0
	s_mul_i32 s42, s88, s43
	v_readlane_b32 s44, v252, 12
	v_and_b32_e32 v41, 60, v0
	v_lshl_add_u32 v56, s43, 6, v2
	s_mul_i32 s43, s85, s43
	s_add_i32 s44, s44, s86
	v_subrev_u32_e32 v0, s43, v41
	v_mov_b32_e32 v2, v1
	v_mov_b32_e32 v3, v1
	s_add_i32 s42, s44, s42
	v_add_u32_e32 v43, s44, v0
	v_mov_b32_e32 v0, v1
	v_mov_b64_e32 v[10:11], v[2:3]
	s_ashr_i32 s43, s42, 31
	v_cmp_gt_i32_e32 vcc, s70, v56
	v_mov_b32_e32 v42, 1.0
	v_mov_b64_e32 v[8:9], v[0:1]
	s_and_saveexec_b64 s[44:45], vcc
	s_cbranch_execz .LBB0_454
	v_mov_b32_e32 v2, v1
	v_mov_b32_e32 v3, v1
	v_mov_b32_e32 v0, v1
	v_mov_b64_e32 v[10:11], v[2:3]
	v_cmp_gt_i32_e32 vcc, s37, v43
	v_mov_b64_e32 v[8:9], v[0:1]
	s_and_saveexec_b64 s[64:65], vcc
	s_cbranch_execz .LBB0_444
	v_mad_i64_i32 v[2:3], s[66:67], v56, s37, 0
	v_lshl_add_u64 v[2:3], v[2:3], 2, s[0:1]
	v_lshl_add_u64 v[2:3], s[42:43], 2, v[2:3]
	v_lshlrev_b32_e32 v0, 2, v41
	v_lshl_add_u64 v[2:3], v[2:3], 0, v[0:1]
	global_load_dwordx4 v[8:11], v[2:3], off
	s_cmp_lt_i32 s70, 64
	s_cbranch_scc1 .Lcpf_skip7
	s_lshl_b32 s100, s37, 7
	s_mov_b32 s101, 0
	v_lshl_add_u64 v[70:71], s[100:101], 0, v[2:3]
	global_load_dwordx4 v[66:69], v[70:71], off

.LBB0_918:
	s_add_i32 s0, s64, 63
	s_lshr_b32 s67, s0, 6
	s_add_i32 s0, s70, 63
	s_ashr_i32 s42, s0, 6
	s_mul_i32 s0, s69, 37
	s_add_i32 s0, s0, s68
	s_ashr_i32 s43, s0, 31
	s_abs_i32 s0, s0
	v_readlane_b32 s1, v252, 1
	s_mul_hi_u32 s1, s0, s1
	v_readlane_b32 s4, v252, 0
	s_mul_i32 s1, s1, s4
	s_sub_i32 s0, s0, s1
	s_sub_i32 s1, s0, s4
	s_cmp_ge_u32 s0, s4
	s_cselect_b32 s0, s1, s0
	s_sub_i32 s1, s0, s4
	s_cmp_ge_u32 s0, s4
	s_cselect_b32 s0, s1, s0
	s_xor_b32 s44, s0, s43
	s_sub_i32 s76, s44, s43
	s_mul_i32 s67, s67, s42
	s_cmp_lg_u64 s[30:31], 0
	s_cselect_b64 s[0:1], -1, 0
	s_cmp_lt_i32 s76, s67
	s_cselect_b64 s[4:5], -1, 0
	s_and_b64 vcc, exec, s[4:5]
	s_cbranch_vccz .LBB0_963
	s_abs_i32 s36, s42
	v_cvt_f32_u32_e32 v0, s36
	s_sub_i32 s39, 0, s36
	s_abs_i32 s38, s76
	s_xor_b32 s37, s76, s42
	v_rcp_iflag_f32_e32 v0, v0
	s_ashr_i32 s37, s37, 31
	v_mov_b32_e32 v2, v202
	v_mul_f32_e32 v0, 0x4f7ffffe, v0
	v_cvt_u32_f32_e32 v0, v0
	v_ashrrev_i32_e32 v3, 4, v2
	v_mov_b32_e32 v46, 1.0
	v_readfirstlane_b32 s40, v0
	s_mul_i32 s39, s39, s40
	s_mul_hi_u32 s39, s40, s39
	s_add_i32 s40, s40, s39
	s_mul_hi_u32 s39, s38, s40
	s_mul_i32 s40, s39, s36
	s_sub_i32 s38, s38, s40
	s_add_i32 s41, s39, 1
	s_sub_i32 s40, s38, s36
	s_cmp_ge_u32 s38, s36
	s_cselect_b32 s39, s41, s39
	s_cselect_b32 s38, s40, s38
	s_add_i32 s40, s39, 1
	s_cmp_ge_u32 s38, s36
	s_cselect_b32 s36, s40, s39
	s_xor_b32 s36, s36, s37
	s_sub_i32 s37, s36, s37
	s_mul_i32 s36, s37, s42
	s_sub_i32 s36, s76, s36
	v_lshlrev_b32_e32 v0, 2, v2
	v_lshl_add_u32 v56, s37, 6, v3
	v_mov_b32_e32 v2, v1
	v_mov_b32_e32 v3, v1
	s_lshl_b32 s36, s36, 6
	v_and_b32_e32 v41, 60, v0
	v_mov_b32_e32 v0, v1
	v_mov_b64_e32 v[22:23], v[2:3]
	v_or_b32_e32 v43, s36, v41
	s_ashr_i32 s37, s36, 31
	v_cmp_gt_i32_e32 vcc, s64, v56
	v_mov_b64_e32 v[20:21], v[0:1]
	s_and_saveexec_b64 s[38:39], vcc
	s_cbranch_execz .LBB0_929
	v_mov_b32_e32 v2, v1
	v_mov_b32_e32 v3, v1
	v_mov_b32_e32 v0, v1
	v_mov_b64_e32 v[22:23], v[2:3]
	v_cmp_gt_i32_e32 vcc, s70, v43
	v_mov_b64_e32 v[20:21], v[0:1]
	s_and_saveexec_b64 s[40:41], vcc
	s_cbranch_execz .LBB0_922
	v_mad_i64_i32 v[2:3], s[78:79], v56, s70, 0
	v_lshl_add_u64 v[2:3], v[2:3], 2, s[10:11]
	v_lshl_add_u64 v[2:3], s[36:37], 2, v[2:3]
	v_lshlrev_b32_e32 v0, 2, v41
	v_lshl_add_u64 v[2:3], v[2:3], 0, v[0:1]
	global_load_dwordx4 v[20:23], v[2:3], off
	s_cmp_lt_i32 s64, 64
	s_cbranch_scc1 .Lcpf_skip8
	s_lshl_b32 s100, s70, 7
	s_mov_b32 s101, 0
	v_lshl_add_u64 v[70:71], s[100:101], 0, v[2:3]
	global_load_dwordx4 v[66:69], v[70:71], off
.Lcpf_skip8:
.LBB0_922:
	s_or_b64 exec, exec, s[40:41]
	s_andn2_b64 vcc, exec, s[0:1]
	s_cbranch_vccnz .LBB0_1190
	v_ashrrev_i32_e32 v57, 31, v56
	v_lshl_add_u64 v[2:3], v[56:57], 2, s[30:31]
	global_load_dword v0, v[2:3], off
	s_movk_i32 s78, 0xfff
	s_cmp_gt_i32 s72, 1
	s_mov_b64 s[40:41], -1
	s_cbranch_scc0 .LBB0_925

.LBB0_941:
	s_abs_i32 s36, s42
	s_waitcnt vmcnt(0)
	v_cvt_f32_u32_e32 v0, s36
	s_sub_i32 s39, 0, s36
	s_abs_i32 s38, s45
	s_xor_b32 s37, s45, s42
	v_rcp_iflag_f32_e32 v0, v0
	s_ashr_i32 s37, s37, 31
	v_mov_b32_e32 v2, v202
	v_mul_f32_e32 v0, 0x4f7ffffe, v0
	v_cvt_u32_f32_e32 v0, v0
	v_ashrrev_i32_e32 v3, 4, v2
	v_mov_b32_e32 v40, 1.0
	v_readfirstlane_b32 s40, v0
	s_mul_i32 s39, s39, s40
	s_mul_hi_u32 s39, s40, s39
	s_add_i32 s40, s40, s39
	s_mul_hi_u32 s39, s38, s40
	s_mul_i32 s40, s39, s36
	s_sub_i32 s38, s38, s40
	s_add_i32 s41, s39, 1
	s_sub_i32 s40, s38, s36
	s_cmp_ge_u32 s38, s36
	s_cselect_b32 s39, s41, s39
	s_cselect_b32 s38, s40, s38
	s_add_i32 s40, s39, 1
	s_cmp_ge_u32 s38, s36
	s_cselect_b32 s36, s40, s39
	s_xor_b32 s36, s36, s37
	s_sub_i32 s37, s36, s37
	s_mul_i32 s36, s37, s42
	s_sub_i32 s36, s45, s36
	v_lshlrev_b32_e32 v0, 2, v2
	v_lshl_add_u32 v56, s37, 6, v3
	v_mov_b32_e32 v2, v1
	v_mov_b32_e32 v3, v1
	s_lshl_b32 s36, s36, 6
	v_and_b32_e32 v41, 60, v0
	v_mov_b32_e32 v0, v1
	v_mov_b64_e32 v[14:15], v[2:3]
	v_or_b32_e32 v43, s36, v41
	s_ashr_i32 s37, s36, 31
	v_cmp_gt_i32_e32 vcc, s64, v56
	v_mov_b64_e32 v[12:13], v[0:1]
	s_and_saveexec_b64 s[38:39], vcc
	s_cbranch_execz .LBB0_951
	v_mov_b32_e32 v2, v1
	v_mov_b32_e32 v3, v1
	v_mov_b32_e32 v0, v1
	v_mov_b64_e32 v[14:15], v[2:3]
	v_cmp_gt_i32_e32 vcc, s70, v43
	v_mov_b64_e32 v[12:13], v[0:1]
	s_and_saveexec_b64 s[40:41], vcc
	s_cbranch_execz .LBB0_944
	v_mad_i64_i32 v[2:3], s[78:79], v56, s70, 0
	v_lshl_add_u64 v[2:3], v[2:3], 2, s[10:11]
	v_lshl_add_u64 v[2:3], s[36:37], 2, v[2:3]
	v_lshlrev_b32_e32 v0, 2, v41
	v_lshl_add_u64 v[2:3], v[2:3], 0, v[0:1]
	global_load_dwordx4 v[12:15], v[2:3], off
	s_cmp_lt_i32 s64, 64
	s_cbranch_scc1 .Lcpf_skip9
	s_lshl_b32 s100, s70, 7
	s_mov_b32 s101, 0
	v_lshl_add_u64 v[70:71], s[100:101], 0, v[2:3]
	global_load_dwordx4 v[66:69], v[70:71], off

.LBB0_964:
	s_abs_i32 s36, s42
	s_waitcnt vmcnt(0)
	v_cvt_f32_u32_e32 v0, s36
	s_sub_i32 s39, 0, s36
	s_abs_i32 s38, s45
	s_xor_b32 s37, s45, s42
	v_rcp_iflag_f32_e32 v0, v0
	s_ashr_i32 s37, s37, 31
	v_mov_b32_e32 v2, v202
	v_mul_f32_e32 v0, 0x4f7ffffe, v0
	v_cvt_u32_f32_e32 v0, v0
	v_ashrrev_i32_e32 v3, 4, v2
	v_mov_b32_e32 v44, 1.0
	v_readfirstlane_b32 s40, v0
	s_mul_i32 s39, s39, s40
	s_mul_hi_u32 s39, s40, s39
	s_add_i32 s40, s40, s39
	s_mul_hi_u32 s39, s38, s40
	s_mul_i32 s40, s39, s36
	s_sub_i32 s38, s38, s40
	s_add_i32 s41, s39, 1
	s_sub_i32 s40, s38, s36
	s_cmp_ge_u32 s38, s36
	s_cselect_b32 s39, s41, s39
	s_cselect_b32 s38, s40, s38
	s_add_i32 s40, s39, 1
	s_cmp_ge_u32 s38, s36
	s_cselect_b32 s36, s40, s39
	s_xor_b32 s36, s36, s37
	s_sub_i32 s37, s36, s37
	s_mul_i32 s36, s37, s42
	s_sub_i32 s36, s45, s36
	v_lshlrev_b32_e32 v0, 2, v2
	v_lshl_add_u32 v56, s37, 6, v3
	v_mov_b32_e32 v2, v1
	v_mov_b32_e32 v3, v1
	s_lshl_b32 s36, s36, 6
	v_and_b32_e32 v41, 60, v0
	v_mov_b32_e32 v0, v1
	v_mov_b64_e32 v[18:19], v[2:3]
	v_or_b32_e32 v43, s36, v41
	s_ashr_i32 s37, s36, 31
	v_cmp_gt_i32_e32 vcc, s64, v56
	v_mov_b64_e32 v[16:17], v[0:1]
	s_and_saveexec_b64 s[38:39], vcc
	s_cbranch_execz .LBB0_974
	v_mov_b32_e32 v2, v1
	v_mov_b32_e32 v3, v1
	v_mov_b32_e32 v0, v1
	v_mov_b64_e32 v[18:19], v[2:3]
	v_cmp_gt_i32_e32 vcc, s70, v43
	v_mov_b64_e32 v[16:17], v[0:1]
	s_and_saveexec_b64 s[40:41], vcc
	s_cbranch_execz .LBB0_967
	v_mad_i64_i32 v[2:3], s[78:79], v56, s70, 0
	v_lshl_add_u64 v[2:3], v[2:3], 2, s[10:11]
	v_lshl_add_u64 v[2:3], s[36:37], 2, v[2:3]
	v_lshlrev_b32_e32 v0, 2, v41
	v_lshl_add_u64 v[2:3], v[2:3], 0, v[0:1]
	global_load_dwordx4 v[16:19], v[2:3], off
	s_cmp_lt_i32 s64, 64
	s_cbranch_scc1 .Lcpf_skip10
	s_lshl_b32 s100, s70, 7
	s_mov_b32 s101, 0
	v_lshl_add_u64 v[70:71], s[100:101], 0, v[2:3]
	global_load_dwordx4 v[66:69], v[70:71], off

.LBB0_986:
	s_abs_i32 s36, s42
	s_waitcnt vmcnt(0)
	v_cvt_f32_u32_e32 v0, s36
	s_sub_i32 s39, 0, s36
	s_abs_i32 s38, s45
	s_xor_b32 s37, s45, s42
	v_rcp_iflag_f32_e32 v0, v0
	s_ashr_i32 s37, s37, 31
	v_mov_b32_e32 v2, v202
	v_mul_f32_e32 v0, 0x4f7ffffe, v0
	v_cvt_u32_f32_e32 v0, v0
	v_ashrrev_i32_e32 v3, 4, v2
	v_mov_b32_e32 v42, 1.0
	v_readfirstlane_b32 s40, v0
	s_mul_i32 s39, s39, s40
	s_mul_hi_u32 s39, s40, s39
	s_add_i32 s40, s40, s39
	s_mul_hi_u32 s39, s38, s40
	s_mul_i32 s40, s39, s36
	s_sub_i32 s38, s38, s40
	s_add_i32 s41, s39, 1
	s_sub_i32 s40, s38, s36
	s_cmp_ge_u32 s38, s36
	s_cselect_b32 s39, s41, s39
	s_cselect_b32 s38, s40, s38
	s_add_i32 s40, s39, 1
	s_cmp_ge_u32 s38, s36
	s_cselect_b32 s36, s40, s39
	s_xor_b32 s36, s36, s37
	s_sub_i32 s37, s36, s37
	s_mul_i32 s36, s37, s42
	s_sub_i32 s36, s45, s36
	v_lshlrev_b32_e32 v0, 2, v2
	v_lshl_add_u32 v56, s37, 6, v3
	v_mov_b32_e32 v2, v1
	v_mov_b32_e32 v3, v1
	s_lshl_b32 s36, s36, 6
	v_and_b32_e32 v41, 60, v0
	v_mov_b32_e32 v0, v1
	s_waitcnt lgkmcnt(0)
	v_mov_b64_e32 v[10:11], v[2:3]
	v_or_b32_e32 v43, s36, v41
	s_ashr_i32 s37, s36, 31
	v_cmp_gt_i32_e32 vcc, s64, v56
	v_mov_b64_e32 v[8:9], v[0:1]
	s_and_saveexec_b64 s[38:39], vcc
	s_cbranch_execz .LBB0_996
	v_mov_b32_e32 v2, v1
	v_mov_b32_e32 v3, v1
	v_mov_b32_e32 v0, v1
	v_mov_b64_e32 v[10:11], v[2:3]
	v_cmp_gt_i32_e32 vcc, s70, v43
	v_mov_b64_e32 v[8:9], v[0:1]
	s_and_saveexec_b64 s[40:41], vcc
	s_cbranch_execz .LBB0_989
	v_mad_i64_i32 v[2:3], s[78:79], v56, s70, 0
	v_lshl_add_u64 v[2:3], v[2:3], 2, s[10:11]
	v_lshl_add_u64 v[2:3], s[36:37], 2, v[2:3]
	v_lshlrev_b32_e32 v0, 2, v41
	v_lshl_add_u64 v[2:3], v[2:3], 0, v[0:1]
	global_load_dwordx4 v[8:11], v[2:3], off
	s_cmp_lt_i32 s64, 64
	s_cbranch_scc1 .Lcpf_skip11
	s_lshl_b32 s100, s70, 7
	s_mov_b32 s101, 0
	v_lshl_add_u64 v[70:71], s[100:101], 0, v[2:3]
	global_load_dwordx4 v[66:69], v[70:71], off

.LBB0_1021:
	s_or_b64 exec, exec, s[4:5]
	s_add_i32 s85, s76, s94
	s_waitcnt lgkmcnt(0)
	s_barrier
	s_cmp_ge_i32 s85, s67
	s_cselect_b64 s[4:5], -1, 0
	s_and_b64 vcc, exec, s[4:5]
	s_cbranch_vccnz .LBB0_1049
	s_abs_i32 s37, s85
	s_mul_hi_u32 s38, s37, s83
	s_mul_i32 s39, s38, s77
	s_ashr_i32 s36, s85, 31
	s_sub_i32 s37, s37, s39
	s_xor_b32 s36, s36, s78
	s_add_i32 s39, s38, 1
	s_sub_i32 s40, s37, s77
	s_cmp_ge_u32 s37, s77
	s_cselect_b32 s38, s39, s38
	s_cselect_b32 s37, s40, s37
	s_add_i32 s39, s38, 1
	s_cmp_ge_u32 s37, s77
	v_mov_b32_e32 v0, v202
	s_cselect_b32 s37, s39, s38
	s_xor_b32 s37, s37, s36
	s_sub_i32 s37, s37, s36
	v_ashrrev_i32_e32 v2, 4, v0
	v_lshlrev_b32_e32 v0, 2, v0
	s_mul_i32 s36, s84, s37
	v_and_b32_e32 v41, 60, v0
	v_lshl_add_u32 v56, s37, 6, v2
	s_mul_i32 s37, s79, s37
	s_add_i32 s38, s29, s82
	v_subrev_u32_e32 v0, s37, v41
	v_mov_b32_e32 v2, v1
	v_mov_b32_e32 v3, v1
	s_add_i32 s36, s38, s36
	v_add_u32_e32 v43, s38, v0
	v_mov_b32_e32 v0, v1
	v_mov_b64_e32 v[22:23], v[2:3]
	s_ashr_i32 s37, s36, 31
	v_cmp_gt_i32_e32 vcc, s64, v56
	v_mov_b32_e32 v46, 1.0
	v_mov_b64_e32 v[20:21], v[0:1]
	s_and_saveexec_b64 s[38:39], vcc
	s_cbranch_execz .LBB0_1035
	v_mov_b32_e32 v2, v1
	v_mov_b32_e32 v3, v1
	v_mov_b32_e32 v0, v1
	v_mov_b64_e32 v[22:23], v[2:3]
	v_cmp_gt_i32_e32 vcc, s70, v43
	v_mov_b64_e32 v[20:21], v[0:1]
	s_and_saveexec_b64 s[40:41], vcc
	s_cbranch_execz .LBB0_1025
	v_mad_i64_i32 v[2:3], s[42:43], v56, s70, 0
	v_lshl_add_u64 v[2:3], v[2:3], 2, s[10:11]
	v_lshl_add_u64 v[2:3], s[36:37], 2, v[2:3]
	v_lshlrev_b32_e32 v0, 2, v41
	v_lshl_add_u64 v[2:3], v[2:3], 0, v[0:1]
	global_load_dwordx4 v[20:23], v[2:3], off
	s_cmp_lt_i32 s64, 64
	s_cbranch_scc1 .Lcpf_skip12
	s_lshl_b32 s100, s70, 7
	s_mov_b32 s101, 0
	v_lshl_add_u64 v[70:71], s[100:101], 0, v[2:3]
	global_load_dwordx4 v[66:69], v[70:71], off
.Lcpf_skip12:
.LBB0_1025:
	s_or_b64 exec, exec, s[40:41]
	s_andn2_b64 vcc, exec, s[0:1]
	s_cbranch_vccnz .LBB0_1030
	v_ashrrev_i32_e32 v57, 31, v56
	v_lshl_add_u64 v[2:3], v[56:57], 2, s[30:31]
	global_load_dword v0, v[2:3], off
	s_cmp_lt_i32 s72, 2
	s_mov_b64 s[40:41], -1
	s_cbranch_scc1 .LBB0_1031

.LBB0_1063:
	s_or_b64 exec, exec, s[36:37]
	s_waitcnt lgkmcnt(0)
	s_barrier
	s_mul_i32 s36, s28, 5
	s_add_i32 s36, s36, s76
	s_cmp_ge_i32 s36, s67
	s_cbranch_scc1 .LBB0_1091
	s_ashr_i32 s37, s36, 31
	s_abs_i32 s36, s36
	s_mul_hi_u32 s38, s36, s83
	s_mul_i32 s39, s38, s77
	s_sub_i32 s36, s36, s39
	s_xor_b32 s37, s37, s78
	s_add_i32 s39, s38, 1
	s_sub_i32 s40, s36, s77
	s_cmp_ge_u32 s36, s77
	s_cselect_b32 s38, s39, s38
	s_cselect_b32 s36, s40, s36
	s_add_i32 s39, s38, 1
	s_cmp_ge_u32 s36, s77
	v_mov_b32_e32 v0, v202
	s_cselect_b32 s36, s39, s38
	s_xor_b32 s36, s36, s37
	s_sub_i32 s37, s36, s37
	v_ashrrev_i32_e32 v2, 4, v0
	v_lshlrev_b32_e32 v0, 2, v0
	s_mul_i32 s36, s84, s37
	s_mul_i32 s38, s28, 0x140
	v_and_b32_e32 v41, 60, v0
	v_lshl_add_u32 v56, s37, 6, v2
	s_mul_i32 s37, s79, s37
	s_add_i32 s38, s38, s82
	v_subrev_u32_e32 v0, s37, v41
	v_mov_b32_e32 v2, v1
	v_mov_b32_e32 v3, v1
	s_add_i32 s36, s38, s36
	v_add_u32_e32 v43, s38, v0
	v_mov_b32_e32 v0, v1
	v_mov_b64_e32 v[18:19], v[2:3]
	s_ashr_i32 s37, s36, 31
	v_cmp_gt_i32_e32 vcc, s64, v56
	v_mov_b32_e32 v44, 1.0
	v_mov_b64_e32 v[16:17], v[0:1]
	s_and_saveexec_b64 s[38:39], vcc
	s_cbranch_execz .LBB0_1077
	v_mov_b32_e32 v2, v1
	v_mov_b32_e32 v3, v1
	v_mov_b32_e32 v0, v1
	v_mov_b64_e32 v[18:19], v[2:3]
	v_cmp_gt_i32_e32 vcc, s70, v43
	v_mov_b64_e32 v[16:17], v[0:1]
	s_and_saveexec_b64 s[40:41], vcc
	s_cbranch_execz .LBB0_1067
	v_mad_i64_i32 v[2:3], s[42:43], v56, s70, 0
	v_lshl_add_u64 v[2:3], v[2:3], 2, s[10:11]
	v_lshl_add_u64 v[2:3], s[36:37], 2, v[2:3]
	v_lshlrev_b32_e32 v0, 2, v41
	v_lshl_add_u64 v[2:3], v[2:3], 0, v[0:1]
	global_load_dwordx4 v[16:19], v[2:3], off
	s_cmp_lt_i32 s64, 64
	s_cbranch_scc1 .Lcpf_skip13
	s_lshl_b32 s100, s70, 7
	s_mov_b32 s101, 0
	v_lshl_add_u64 v[70:71], s[100:101], 0, v[2:3]
	global_load_dwordx4 v[66:69], v[70:71], off

.LBB0_1105:
	s_or_b64 exec, exec, s[36:37]
	s_waitcnt lgkmcnt(0)
	s_barrier
	s_mul_i32 s36, s28, 6
	s_add_i32 s36, s36, s76
	s_cmp_ge_i32 s36, s67
	s_cbranch_scc1 .LBB0_1133
	s_ashr_i32 s37, s36, 31
	s_abs_i32 s36, s36
	s_mul_hi_u32 s38, s36, s83
	s_mul_i32 s39, s38, s77
	s_sub_i32 s36, s36, s39
	s_xor_b32 s37, s37, s78
	s_add_i32 s39, s38, 1
	s_sub_i32 s40, s36, s77
	s_cmp_ge_u32 s36, s77
	s_cselect_b32 s38, s39, s38
	s_cselect_b32 s36, s40, s36
	s_add_i32 s39, s38, 1
	s_cmp_ge_u32 s36, s77
	v_mov_b32_e32 v0, v202
	s_cselect_b32 s36, s39, s38
	s_xor_b32 s36, s36, s37
	s_sub_i32 s37, s36, s37
	v_ashrrev_i32_e32 v2, 4, v0
	v_lshlrev_b32_e32 v0, 2, v0
	s_mul_i32 s36, s84, s37
	s_mul_i32 s38, s28, 0x180
	v_and_b32_e32 v41, 60, v0
	v_lshl_add_u32 v56, s37, 6, v2
	s_mul_i32 s37, s79, s37
	s_add_i32 s38, s38, s82
	v_subrev_u32_e32 v0, s37, v41
	v_mov_b32_e32 v2, v1
	v_mov_b32_e32 v3, v1
	s_add_i32 s36, s38, s36
	v_add_u32_e32 v43, s38, v0
	v_mov_b32_e32 v0, v1
	v_mov_b64_e32 v[14:15], v[2:3]
	s_ashr_i32 s37, s36, 31
	v_cmp_gt_i32_e32 vcc, s64, v56
	v_mov_b32_e32 v40, 1.0
	v_mov_b64_e32 v[12:13], v[0:1]
	s_and_saveexec_b64 s[38:39], vcc
	s_cbranch_execz .LBB0_1119
	v_mov_b32_e32 v2, v1
	v_mov_b32_e32 v3, v1
	v_mov_b32_e32 v0, v1
	v_mov_b64_e32 v[14:15], v[2:3]
	v_cmp_gt_i32_e32 vcc, s70, v43
	v_mov_b64_e32 v[12:13], v[0:1]
	s_and_saveexec_b64 s[40:41], vcc
	s_cbranch_execz .LBB0_1109
	v_mad_i64_i32 v[2:3], s[42:43], v56, s70, 0
	v_lshl_add_u64 v[2:3], v[2:3], 2, s[10:11]
	v_lshl_add_u64 v[2:3], s[36:37], 2, v[2:3]
	v_lshlrev_b32_e32 v0, 2, v41
	v_lshl_add_u64 v[2:3], v[2:3], 0, v[0:1]
	global_load_dwordx4 v[12:15], v[2:3], off
	s_cmp_lt_i32 s64, 64
	s_cbranch_scc1 .Lcpf_skip14
	s_lshl_b32 s100, s70, 7
	s_mov_b32 s101, 0
	v_lshl_add_u64 v[70:71], s[100:101], 0, v[2:3]
	global_load_dwordx4 v[66:69], v[70:71], off

.LBB0_1147:
	s_or_b64 exec, exec, s[36:37]
	s_waitcnt lgkmcnt(0)
	s_barrier
	s_mul_i32 s36, s28, 7
	s_add_i32 s36, s36, s76
	s_cmp_ge_i32 s36, s67
	s_cbranch_scc1 .LBB0_1175
	s_ashr_i32 s37, s36, 31
	s_abs_i32 s36, s36
	s_mul_hi_u32 s38, s36, s83
	s_mul_i32 s39, s38, s77
	s_sub_i32 s36, s36, s39
	s_xor_b32 s37, s37, s78
	s_add_i32 s39, s38, 1
	s_sub_i32 s40, s36, s77
	s_cmp_ge_u32 s36, s77
	s_cselect_b32 s38, s39, s38
	s_cselect_b32 s36, s40, s36
	s_add_i32 s39, s38, 1
	s_cmp_ge_u32 s36, s77
	v_mov_b32_e32 v0, v202
	s_cselect_b32 s36, s39, s38
	s_xor_b32 s36, s36, s37
	s_sub_i32 s37, s36, s37
	v_ashrrev_i32_e32 v2, 4, v0
	v_lshlrev_b32_e32 v0, 2, v0
	s_mul_i32 s36, s84, s37
	s_mul_i32 s38, s28, 0x1c0
	v_and_b32_e32 v41, 60, v0
	v_lshl_add_u32 v56, s37, 6, v2
	s_mul_i32 s37, s79, s37
	s_add_i32 s38, s38, s82
	v_subrev_u32_e32 v0, s37, v41
	v_mov_b32_e32 v2, v1
	v_mov_b32_e32 v3, v1
	s_add_i32 s36, s38, s36
	v_add_u32_e32 v43, s38, v0
	v_mov_b32_e32 v0, v1
	v_mov_b64_e32 v[10:11], v[2:3]
	s_ashr_i32 s37, s36, 31
	v_cmp_gt_i32_e32 vcc, s64, v56
	v_mov_b32_e32 v42, 1.0
	v_mov_b64_e32 v[8:9], v[0:1]
	s_and_saveexec_b64 s[38:39], vcc
	s_cbranch_execz .LBB0_1161
	v_mov_b32_e32 v2, v1
	v_mov_b32_e32 v3, v1
	v_mov_b32_e32 v0, v1
	v_mov_b64_e32 v[10:11], v[2:3]
	v_cmp_gt_i32_e32 vcc, s70, v43
	v_mov_b64_e32 v[8:9], v[0:1]
	s_and_saveexec_b64 s[40:41], vcc
	s_cbranch_execz .LBB0_1151
	v_mad_i64_i32 v[2:3], s[42:43], v56, s70, 0
	v_lshl_add_u64 v[2:3], v[2:3], 2, s[10:11]
	v_lshl_add_u64 v[2:3], s[36:37], 2, v[2:3]
	v_lshlrev_b32_e32 v0, 2, v41
	v_lshl_add_u64 v[2:3], v[2:3], 0, v[0:1]
	global_load_dwordx4 v[8:11], v[2:3], off
	s_cmp_lt_i32 s64, 64
	s_cbranch_scc1 .Lcpf_skip15
	s_lshl_b32 s100, s70, 7
	s_mov_b32 s101, 0
	v_lshl_add_u64 v[70:71], s[100:101], 0, v[2:3]
	global_load_dwordx4 v[66:69], v[70:71], off

.LBB0_1270:
	s_add_i32 s30, s64, 63
	s_lshr_b32 s72, s30, 6
	s_add_i32 s30, s68, 63
	s_ashr_i32 s42, s30, 6
	s_mul_i32 s30, s67, 37
	s_add_i32 s30, s30, s66
	s_ashr_i32 s43, s30, 31
	s_abs_i32 s30, s30
	v_readlane_b32 s31, v252, 1
	s_mul_hi_u32 s31, s30, s31
	v_readlane_b32 s34, v252, 0
	s_mul_i32 s31, s31, s34
	s_sub_i32 s30, s30, s31
	s_sub_i32 s31, s30, s34
	s_cmp_ge_u32 s30, s34
	s_cselect_b32 s30, s31, s30
	s_sub_i32 s31, s30, s34
	s_cmp_ge_u32 s30, s34
	s_cselect_b32 s30, s31, s30
	s_xor_b32 s44, s30, s43
	s_sub_i32 s76, s44, s43
	s_mul_i32 s72, s72, s42
	s_cmp_lg_u64 s[8:9], 0
	s_cselect_b64 s[30:31], -1, 0
	s_cmp_lt_i32 s76, s72
	s_cselect_b64 s[34:35], -1, 0
	s_and_b64 vcc, exec, s[34:35]
	s_cbranch_vccz .LBB0_1315
	s_abs_i32 s36, s42
	v_cvt_f32_u32_e32 v0, s36
	s_sub_i32 s39, 0, s36
	s_abs_i32 s38, s76
	s_xor_b32 s37, s76, s42
	v_rcp_iflag_f32_e32 v0, v0
	s_ashr_i32 s37, s37, 31
	v_mov_b32_e32 v2, v202
	v_mul_f32_e32 v0, 0x4f7ffffe, v0
	v_cvt_u32_f32_e32 v0, v0
	v_ashrrev_i32_e32 v3, 4, v2
	v_mov_b32_e32 v46, 1.0
	v_readfirstlane_b32 s40, v0
	s_mul_i32 s39, s39, s40
	s_mul_hi_u32 s39, s40, s39
	s_add_i32 s40, s40, s39
	s_mul_hi_u32 s39, s38, s40
	s_mul_i32 s40, s39, s36
	s_sub_i32 s38, s38, s40
	s_add_i32 s41, s39, 1
	s_sub_i32 s40, s38, s36
	s_cmp_ge_u32 s38, s36
	s_cselect_b32 s39, s41, s39
	s_cselect_b32 s38, s40, s38
	s_add_i32 s40, s39, 1
	s_cmp_ge_u32 s38, s36
	s_cselect_b32 s36, s40, s39
	s_xor_b32 s36, s36, s37
	s_sub_i32 s37, s36, s37
	s_mul_i32 s36, s37, s42
	s_sub_i32 s36, s76, s36
	v_lshlrev_b32_e32 v0, 2, v2
	v_lshl_add_u32 v56, s37, 6, v3
	v_mov_b32_e32 v2, v1
	v_mov_b32_e32 v3, v1
	s_lshl_b32 s36, s36, 6
	v_and_b32_e32 v41, 60, v0
	v_mov_b32_e32 v0, v1
	v_mov_b64_e32 v[22:23], v[2:3]
	v_or_b32_e32 v43, s36, v41
	s_ashr_i32 s37, s36, 31
	v_cmp_gt_i32_e32 vcc, s64, v56
	v_mov_b64_e32 v[20:21], v[0:1]
	s_and_saveexec_b64 s[38:39], vcc
	s_cbranch_execz .LBB0_1281
	v_mov_b32_e32 v2, v1
	v_mov_b32_e32 v3, v1
	v_mov_b32_e32 v0, v1
	v_mov_b64_e32 v[22:23], v[2:3]
	v_cmp_gt_i32_e32 vcc, s68, v43
	v_mov_b64_e32 v[20:21], v[0:1]
	s_and_saveexec_b64 s[40:41], vcc
	s_cbranch_execz .LBB0_1274
	v_mad_i64_i32 v[2:3], s[78:79], v56, s68, 0
	v_lshl_add_u64 v[2:3], v[2:3], 2, s[4:5]
	v_lshl_add_u64 v[2:3], s[36:37], 2, v[2:3]
	v_lshlrev_b32_e32 v0, 2, v41
	v_lshl_add_u64 v[2:3], v[2:3], 0, v[0:1]
	global_load_dwordx4 v[20:23], v[2:3], off
	s_cmp_lt_i32 s64, 64
	s_cbranch_scc1 .Lcpf_skip16
	s_lshl_b32 s100, s68, 7
	s_mov_b32 s101, 0
	v_lshl_add_u64 v[70:71], s[100:101], 0, v[2:3]
	global_load_dwordx4 v[66:69], v[70:71], off
.Lcpf_skip16:
.LBB0_1274:
	s_or_b64 exec, exec, s[40:41]
	s_andn2_b64 vcc, exec, s[30:31]
	s_cbranch_vccnz .LBB0_1542
	v_ashrrev_i32_e32 v57, 31, v56
	v_lshl_add_u64 v[2:3], v[56:57], 2, s[8:9]
	global_load_dword v0, v[2:3], off
	s_movk_i32 s78, 0xfff
	s_cmp_gt_i32 s70, 1
	s_mov_b64 s[40:41], -1
	s_cbranch_scc0 .LBB0_1277

.LBB0_1293:
	s_abs_i32 s36, s42
	s_waitcnt vmcnt(0)
	v_cvt_f32_u32_e32 v0, s36
	s_sub_i32 s39, 0, s36
	s_abs_i32 s38, s45
	s_xor_b32 s37, s45, s42
	v_rcp_iflag_f32_e32 v0, v0
	s_ashr_i32 s37, s37, 31
	v_mov_b32_e32 v2, v202
	v_mul_f32_e32 v0, 0x4f7ffffe, v0
	v_cvt_u32_f32_e32 v0, v0
	v_ashrrev_i32_e32 v3, 4, v2
	v_mov_b32_e32 v40, 1.0
	v_readfirstlane_b32 s40, v0
	s_mul_i32 s39, s39, s40
	s_mul_hi_u32 s39, s40, s39
	s_add_i32 s40, s40, s39
	s_mul_hi_u32 s39, s38, s40
	s_mul_i32 s40, s39, s36
	s_sub_i32 s38, s38, s40
	s_add_i32 s41, s39, 1
	s_sub_i32 s40, s38, s36
	s_cmp_ge_u32 s38, s36
	s_cselect_b32 s39, s41, s39
	s_cselect_b32 s38, s40, s38
	s_add_i32 s40, s39, 1
	s_cmp_ge_u32 s38, s36
	s_cselect_b32 s36, s40, s39
	s_xor_b32 s36, s36, s37
	s_sub_i32 s37, s36, s37
	s_mul_i32 s36, s37, s42
	s_sub_i32 s36, s45, s36
	v_lshlrev_b32_e32 v0, 2, v2
	v_lshl_add_u32 v56, s37, 6, v3
	v_mov_b32_e32 v2, v1
	v_mov_b32_e32 v3, v1
	s_lshl_b32 s36, s36, 6
	v_and_b32_e32 v41, 60, v0
	v_mov_b32_e32 v0, v1
	v_mov_b64_e32 v[14:15], v[2:3]
	v_or_b32_e32 v43, s36, v41
	s_ashr_i32 s37, s36, 31
	v_cmp_gt_i32_e32 vcc, s64, v56
	v_mov_b64_e32 v[12:13], v[0:1]
	s_and_saveexec_b64 s[38:39], vcc
	s_cbranch_execz .LBB0_1303
	v_mov_b32_e32 v2, v1
	v_mov_b32_e32 v3, v1
	v_mov_b32_e32 v0, v1
	v_mov_b64_e32 v[14:15], v[2:3]
	v_cmp_gt_i32_e32 vcc, s68, v43
	v_mov_b64_e32 v[12:13], v[0:1]
	s_and_saveexec_b64 s[40:41], vcc
	s_cbranch_execz .LBB0_1296
	v_mad_i64_i32 v[2:3], s[78:79], v56, s68, 0
	v_lshl_add_u64 v[2:3], v[2:3], 2, s[4:5]
	v_lshl_add_u64 v[2:3], s[36:37], 2, v[2:3]
	v_lshlrev_b32_e32 v0, 2, v41
	v_lshl_add_u64 v[2:3], v[2:3], 0, v[0:1]
	global_load_dwordx4 v[12:15], v[2:3], off
	s_cmp_lt_i32 s64, 64
	s_cbranch_scc1 .Lcpf_skip17
	s_lshl_b32 s100, s68, 7
	s_mov_b32 s101, 0
	v_lshl_add_u64 v[70:71], s[100:101], 0, v[2:3]
	global_load_dwordx4 v[66:69], v[70:71], off

.LBB0_1316:
	s_abs_i32 s36, s42
	s_waitcnt vmcnt(0)
	v_cvt_f32_u32_e32 v0, s36
	s_sub_i32 s39, 0, s36
	s_abs_i32 s38, s45
	s_xor_b32 s37, s45, s42
	v_rcp_iflag_f32_e32 v0, v0
	s_ashr_i32 s37, s37, 31
	v_mov_b32_e32 v2, v202
	v_mul_f32_e32 v0, 0x4f7ffffe, v0
	v_cvt_u32_f32_e32 v0, v0
	v_ashrrev_i32_e32 v3, 4, v2
	v_mov_b32_e32 v44, 1.0
	v_readfirstlane_b32 s40, v0
	s_mul_i32 s39, s39, s40
	s_mul_hi_u32 s39, s40, s39
	s_add_i32 s40, s40, s39
	s_mul_hi_u32 s39, s38, s40
	s_mul_i32 s40, s39, s36
	s_sub_i32 s38, s38, s40
	s_add_i32 s41, s39, 1
	s_sub_i32 s40, s38, s36
	s_cmp_ge_u32 s38, s36
	s_cselect_b32 s39, s41, s39
	s_cselect_b32 s38, s40, s38
	s_add_i32 s40, s39, 1
	s_cmp_ge_u32 s38, s36
	s_cselect_b32 s36, s40, s39
	s_xor_b32 s36, s36, s37
	s_sub_i32 s37, s36, s37
	s_mul_i32 s36, s37, s42
	s_sub_i32 s36, s45, s36
	v_lshlrev_b32_e32 v0, 2, v2
	v_lshl_add_u32 v56, s37, 6, v3
	v_mov_b32_e32 v2, v1
	v_mov_b32_e32 v3, v1
	s_lshl_b32 s36, s36, 6
	v_and_b32_e32 v41, 60, v0
	v_mov_b32_e32 v0, v1
	v_mov_b64_e32 v[18:19], v[2:3]
	v_or_b32_e32 v43, s36, v41
	s_ashr_i32 s37, s36, 31
	v_cmp_gt_i32_e32 vcc, s64, v56
	v_mov_b64_e32 v[16:17], v[0:1]
	s_and_saveexec_b64 s[38:39], vcc
	s_cbranch_execz .LBB0_1326
	v_mov_b32_e32 v2, v1
	v_mov_b32_e32 v3, v1
	v_mov_b32_e32 v0, v1
	v_mov_b64_e32 v[18:19], v[2:3]
	v_cmp_gt_i32_e32 vcc, s68, v43
	v_mov_b64_e32 v[16:17], v[0:1]
	s_and_saveexec_b64 s[40:41], vcc
	s_cbranch_execz .LBB0_1319
	v_mad_i64_i32 v[2:3], s[78:79], v56, s68, 0
	v_lshl_add_u64 v[2:3], v[2:3], 2, s[4:5]
	v_lshl_add_u64 v[2:3], s[36:37], 2, v[2:3]
	v_lshlrev_b32_e32 v0, 2, v41
	v_lshl_add_u64 v[2:3], v[2:3], 0, v[0:1]
	global_load_dwordx4 v[16:19], v[2:3], off
	s_cmp_lt_i32 s64, 64
	s_cbranch_scc1 .Lcpf_skip18
	s_lshl_b32 s100, s68, 7
	s_mov_b32 s101, 0
	v_lshl_add_u64 v[70:71], s[100:101], 0, v[2:3]
	global_load_dwordx4 v[66:69], v[70:71], off

.LBB0_1338:
	s_abs_i32 s36, s42
	s_waitcnt vmcnt(0)
	v_cvt_f32_u32_e32 v0, s36
	s_sub_i32 s39, 0, s36
	s_abs_i32 s38, s45
	s_xor_b32 s37, s45, s42
	v_rcp_iflag_f32_e32 v0, v0
	s_ashr_i32 s37, s37, 31
	v_mov_b32_e32 v2, v202
	v_mul_f32_e32 v0, 0x4f7ffffe, v0
	v_cvt_u32_f32_e32 v0, v0
	v_ashrrev_i32_e32 v3, 4, v2
	v_mov_b32_e32 v42, 1.0
	v_readfirstlane_b32 s40, v0
	s_mul_i32 s39, s39, s40
	s_mul_hi_u32 s39, s40, s39
	s_add_i32 s40, s40, s39
	s_mul_hi_u32 s39, s38, s40
	s_mul_i32 s40, s39, s36
	s_sub_i32 s38, s38, s40
	s_add_i32 s41, s39, 1
	s_sub_i32 s40, s38, s36
	s_cmp_ge_u32 s38, s36
	s_cselect_b32 s39, s41, s39
	s_cselect_b32 s38, s40, s38
	s_add_i32 s40, s39, 1
	s_cmp_ge_u32 s38, s36
	s_cselect_b32 s36, s40, s39
	s_xor_b32 s36, s36, s37
	s_sub_i32 s37, s36, s37
	s_mul_i32 s36, s37, s42
	s_sub_i32 s36, s45, s36
	v_lshlrev_b32_e32 v0, 2, v2
	v_lshl_add_u32 v56, s37, 6, v3
	v_mov_b32_e32 v2, v1
	v_mov_b32_e32 v3, v1
	s_lshl_b32 s36, s36, 6
	v_and_b32_e32 v41, 60, v0
	v_mov_b32_e32 v0, v1
	s_waitcnt lgkmcnt(0)
	v_mov_b64_e32 v[10:11], v[2:3]
	v_or_b32_e32 v43, s36, v41
	s_ashr_i32 s37, s36, 31
	v_cmp_gt_i32_e32 vcc, s64, v56
	v_mov_b64_e32 v[8:9], v[0:1]
	s_and_saveexec_b64 s[38:39], vcc
	s_cbranch_execz .LBB0_1348
	v_mov_b32_e32 v2, v1
	v_mov_b32_e32 v3, v1
	v_mov_b32_e32 v0, v1
	v_mov_b64_e32 v[10:11], v[2:3]
	v_cmp_gt_i32_e32 vcc, s68, v43
	v_mov_b64_e32 v[8:9], v[0:1]
	s_and_saveexec_b64 s[40:41], vcc
	s_cbranch_execz .LBB0_1341
	v_mad_i64_i32 v[2:3], s[78:79], v56, s68, 0
	v_lshl_add_u64 v[2:3], v[2:3], 2, s[4:5]
	v_lshl_add_u64 v[2:3], s[36:37], 2, v[2:3]
	v_lshlrev_b32_e32 v0, 2, v41
	v_lshl_add_u64 v[2:3], v[2:3], 0, v[0:1]
	global_load_dwordx4 v[8:11], v[2:3], off
	s_cmp_lt_i32 s64, 64
	s_cbranch_scc1 .Lcpf_skip19
	s_lshl_b32 s100, s68, 7
	s_mov_b32 s101, 0
	v_lshl_add_u64 v[70:71], s[100:101], 0, v[2:3]
	global_load_dwordx4 v[66:69], v[70:71], off

.LBB0_1373:
	s_or_b64 exec, exec, s[34:35]
	s_add_i32 s85, s76, s94
	s_waitcnt lgkmcnt(0)
	s_barrier
	s_cmp_ge_i32 s85, s72
	s_cselect_b64 s[34:35], -1, 0
	s_and_b64 vcc, exec, s[34:35]
	s_cbranch_vccnz .LBB0_1401
	s_abs_i32 s37, s85
	s_mul_hi_u32 s38, s37, s83
	s_mul_i32 s39, s38, s77
	s_ashr_i32 s36, s85, 31
	s_sub_i32 s37, s37, s39
	s_xor_b32 s36, s36, s78
	s_add_i32 s39, s38, 1
	s_sub_i32 s40, s37, s77
	s_cmp_ge_u32 s37, s77
	s_cselect_b32 s38, s39, s38
	s_cselect_b32 s37, s40, s37
	s_add_i32 s39, s38, 1
	s_cmp_ge_u32 s37, s77
	v_mov_b32_e32 v0, v202
	s_cselect_b32 s37, s39, s38
	s_xor_b32 s37, s37, s36
	s_sub_i32 s37, s37, s36
	v_ashrrev_i32_e32 v2, 4, v0
	v_lshlrev_b32_e32 v0, 2, v0
	s_mul_i32 s36, s84, s37
	v_and_b32_e32 v41, 60, v0
	v_lshl_add_u32 v56, s37, 6, v2
	s_mul_i32 s37, s79, s37
	s_add_i32 s38, s29, s82
	v_subrev_u32_e32 v0, s37, v41
	v_mov_b32_e32 v2, v1
	v_mov_b32_e32 v3, v1
	s_add_i32 s36, s38, s36
	v_add_u32_e32 v43, s38, v0
	v_mov_b32_e32 v0, v1
	v_mov_b64_e32 v[22:23], v[2:3]
	s_ashr_i32 s37, s36, 31
	v_cmp_gt_i32_e32 vcc, s64, v56
	v_mov_b32_e32 v46, 1.0
	v_mov_b64_e32 v[20:21], v[0:1]
	s_and_saveexec_b64 s[38:39], vcc
	s_cbranch_execz .LBB0_1387
	v_mov_b32_e32 v2, v1
	v_mov_b32_e32 v3, v1
	v_mov_b32_e32 v0, v1
	v_mov_b64_e32 v[22:23], v[2:3]
	v_cmp_gt_i32_e32 vcc, s68, v43
	v_mov_b64_e32 v[20:21], v[0:1]
	s_and_saveexec_b64 s[40:41], vcc
	s_cbranch_execz .LBB0_1377
	v_mad_i64_i32 v[2:3], s[42:43], v56, s68, 0
	v_lshl_add_u64 v[2:3], v[2:3], 2, s[4:5]
	v_lshl_add_u64 v[2:3], s[36:37], 2, v[2:3]
	v_lshlrev_b32_e32 v0, 2, v41
	v_lshl_add_u64 v[2:3], v[2:3], 0, v[0:1]
	global_load_dwordx4 v[20:23], v[2:3], off
	s_cmp_lt_i32 s64, 64
	s_cbranch_scc1 .Lcpf_skip20
	s_lshl_b32 s100, s68, 7
	s_mov_b32 s101, 0
	v_lshl_add_u64 v[70:71], s[100:101], 0, v[2:3]
	global_load_dwordx4 v[66:69], v[70:71], off
.Lcpf_skip20:
.LBB0_1377:
	s_or_b64 exec, exec, s[40:41]
	s_andn2_b64 vcc, exec, s[30:31]
	s_cbranch_vccnz .LBB0_1382
	v_ashrrev_i32_e32 v57, 31, v56
	v_lshl_add_u64 v[2:3], v[56:57], 2, s[8:9]
	global_load_dword v0, v[2:3], off
	s_cmp_lt_i32 s70, 2
	s_mov_b64 s[40:41], -1
	s_cbranch_scc1 .LBB0_1383

.LBB0_1415:
	s_or_b64 exec, exec, s[36:37]
	s_waitcnt lgkmcnt(0)
	s_barrier
	s_mul_i32 s36, s28, 5
	s_add_i32 s36, s36, s76
	s_cmp_ge_i32 s36, s72
	s_cbranch_scc1 .LBB0_1443
	s_ashr_i32 s37, s36, 31
	s_abs_i32 s36, s36
	s_mul_hi_u32 s38, s36, s83
	s_mul_i32 s39, s38, s77
	s_sub_i32 s36, s36, s39
	s_xor_b32 s37, s37, s78
	s_add_i32 s39, s38, 1
	s_sub_i32 s40, s36, s77
	s_cmp_ge_u32 s36, s77
	s_cselect_b32 s38, s39, s38
	s_cselect_b32 s36, s40, s36
	s_add_i32 s39, s38, 1
	s_cmp_ge_u32 s36, s77
	v_mov_b32_e32 v0, v202
	s_cselect_b32 s36, s39, s38
	s_xor_b32 s36, s36, s37
	s_sub_i32 s37, s36, s37
	v_ashrrev_i32_e32 v2, 4, v0
	v_lshlrev_b32_e32 v0, 2, v0
	s_mul_i32 s36, s84, s37
	s_mul_i32 s38, s28, 0x140
	v_and_b32_e32 v41, 60, v0
	v_lshl_add_u32 v56, s37, 6, v2
	s_mul_i32 s37, s79, s37
	s_add_i32 s38, s38, s82
	v_subrev_u32_e32 v0, s37, v41
	v_mov_b32_e32 v2, v1
	v_mov_b32_e32 v3, v1
	s_add_i32 s36, s38, s36
	v_add_u32_e32 v43, s38, v0
	v_mov_b32_e32 v0, v1
	v_mov_b64_e32 v[18:19], v[2:3]
	s_ashr_i32 s37, s36, 31
	v_cmp_gt_i32_e32 vcc, s64, v56
	v_mov_b32_e32 v44, 1.0
	v_mov_b64_e32 v[16:17], v[0:1]
	s_and_saveexec_b64 s[38:39], vcc
	s_cbranch_execz .LBB0_1429
	v_mov_b32_e32 v2, v1
	v_mov_b32_e32 v3, v1
	v_mov_b32_e32 v0, v1
	v_mov_b64_e32 v[18:19], v[2:3]
	v_cmp_gt_i32_e32 vcc, s68, v43
	v_mov_b64_e32 v[16:17], v[0:1]
	s_and_saveexec_b64 s[40:41], vcc
	s_cbranch_execz .LBB0_1419
	v_mad_i64_i32 v[2:3], s[42:43], v56, s68, 0
	v_lshl_add_u64 v[2:3], v[2:3], 2, s[4:5]
	v_lshl_add_u64 v[2:3], s[36:37], 2, v[2:3]
	v_lshlrev_b32_e32 v0, 2, v41
	v_lshl_add_u64 v[2:3], v[2:3], 0, v[0:1]
	global_load_dwordx4 v[16:19], v[2:3], off
	s_cmp_lt_i32 s64, 64
	s_cbranch_scc1 .Lcpf_skip21
	s_lshl_b32 s100, s68, 7
	s_mov_b32 s101, 0
	v_lshl_add_u64 v[70:71], s[100:101], 0, v[2:3]
	global_load_dwordx4 v[66:69], v[70:71], off

.LBB0_1457:
	s_or_b64 exec, exec, s[36:37]
	s_waitcnt lgkmcnt(0)
	s_barrier
	s_mul_i32 s36, s28, 6
	s_add_i32 s36, s36, s76
	s_cmp_ge_i32 s36, s72
	s_cbranch_scc1 .LBB0_1485
	s_ashr_i32 s37, s36, 31
	s_abs_i32 s36, s36
	s_mul_hi_u32 s38, s36, s83
	s_mul_i32 s39, s38, s77
	s_sub_i32 s36, s36, s39
	s_xor_b32 s37, s37, s78
	s_add_i32 s39, s38, 1
	s_sub_i32 s40, s36, s77
	s_cmp_ge_u32 s36, s77
	s_cselect_b32 s38, s39, s38
	s_cselect_b32 s36, s40, s36
	s_add_i32 s39, s38, 1
	s_cmp_ge_u32 s36, s77
	v_mov_b32_e32 v0, v202
	s_cselect_b32 s36, s39, s38
	s_xor_b32 s36, s36, s37
	s_sub_i32 s37, s36, s37
	v_ashrrev_i32_e32 v2, 4, v0
	v_lshlrev_b32_e32 v0, 2, v0
	s_mul_i32 s36, s84, s37
	s_mul_i32 s38, s28, 0x180
	v_and_b32_e32 v41, 60, v0
	v_lshl_add_u32 v56, s37, 6, v2
	s_mul_i32 s37, s79, s37
	s_add_i32 s38, s38, s82
	v_subrev_u32_e32 v0, s37, v41
	v_mov_b32_e32 v2, v1
	v_mov_b32_e32 v3, v1
	s_add_i32 s36, s38, s36
	v_add_u32_e32 v43, s38, v0
	v_mov_b32_e32 v0, v1
	v_mov_b64_e32 v[14:15], v[2:3]
	s_ashr_i32 s37, s36, 31
	v_cmp_gt_i32_e32 vcc, s64, v56
	v_mov_b32_e32 v40, 1.0
	v_mov_b64_e32 v[12:13], v[0:1]
	s_and_saveexec_b64 s[38:39], vcc
	s_cbranch_execz .LBB0_1471
	v_mov_b32_e32 v2, v1
	v_mov_b32_e32 v3, v1
	v_mov_b32_e32 v0, v1
	v_mov_b64_e32 v[14:15], v[2:3]
	v_cmp_gt_i32_e32 vcc, s68, v43
	v_mov_b64_e32 v[12:13], v[0:1]
	s_and_saveexec_b64 s[40:41], vcc
	s_cbranch_execz .LBB0_1461
	v_mad_i64_i32 v[2:3], s[42:43], v56, s68, 0
	v_lshl_add_u64 v[2:3], v[2:3], 2, s[4:5]
	v_lshl_add_u64 v[2:3], s[36:37], 2, v[2:3]
	v_lshlrev_b32_e32 v0, 2, v41
	v_lshl_add_u64 v[2:3], v[2:3], 0, v[0:1]
	global_load_dwordx4 v[12:15], v[2:3], off
	s_cmp_lt_i32 s64, 64
	s_cbranch_scc1 .Lcpf_skip22
	s_lshl_b32 s100, s68, 7
	s_mov_b32 s101, 0
	v_lshl_add_u64 v[70:71], s[100:101], 0, v[2:3]
	global_load_dwordx4 v[66:69], v[70:71], off

.LBB0_1499:
	s_or_b64 exec, exec, s[36:37]
	s_waitcnt lgkmcnt(0)
	s_barrier
	s_mul_i32 s36, s28, 7
	s_add_i32 s36, s36, s76
	s_cmp_ge_i32 s36, s72
	s_cbranch_scc1 .LBB0_1527
	s_ashr_i32 s37, s36, 31
	s_abs_i32 s36, s36
	s_mul_hi_u32 s38, s36, s83
	s_mul_i32 s39, s38, s77
	s_sub_i32 s36, s36, s39
	s_xor_b32 s37, s37, s78
	s_add_i32 s39, s38, 1
	s_sub_i32 s40, s36, s77
	s_cmp_ge_u32 s36, s77
	s_cselect_b32 s38, s39, s38
	s_cselect_b32 s36, s40, s36
	s_add_i32 s39, s38, 1
	s_cmp_ge_u32 s36, s77
	v_mov_b32_e32 v0, v202
	s_cselect_b32 s36, s39, s38
	s_xor_b32 s36, s36, s37
	s_sub_i32 s37, s36, s37
	v_ashrrev_i32_e32 v2, 4, v0
	v_lshlrev_b32_e32 v0, 2, v0
	s_mul_i32 s36, s84, s37
	s_mul_i32 s38, s28, 0x1c0
	v_and_b32_e32 v41, 60, v0
	v_lshl_add_u32 v56, s37, 6, v2
	s_mul_i32 s37, s79, s37
	s_add_i32 s38, s38, s82
	v_subrev_u32_e32 v0, s37, v41
	v_mov_b32_e32 v2, v1
	v_mov_b32_e32 v3, v1
	s_add_i32 s36, s38, s36
	v_add_u32_e32 v43, s38, v0
	v_mov_b32_e32 v0, v1
	v_mov_b64_e32 v[10:11], v[2:3]
	s_ashr_i32 s37, s36, 31
	v_cmp_gt_i32_e32 vcc, s64, v56
	v_mov_b32_e32 v42, 1.0
	v_mov_b64_e32 v[8:9], v[0:1]
	s_and_saveexec_b64 s[38:39], vcc
	s_cbranch_execz .LBB0_1513
	v_mov_b32_e32 v2, v1
	v_mov_b32_e32 v3, v1
	v_mov_b32_e32 v0, v1
	v_mov_b64_e32 v[10:11], v[2:3]
	v_cmp_gt_i32_e32 vcc, s68, v43
	v_mov_b64_e32 v[8:9], v[0:1]
	s_and_saveexec_b64 s[40:41], vcc
	s_cbranch_execz .LBB0_1503
	v_mad_i64_i32 v[2:3], s[42:43], v56, s68, 0
	v_lshl_add_u64 v[2:3], v[2:3], 2, s[4:5]
	v_lshl_add_u64 v[2:3], s[36:37], 2, v[2:3]
	v_lshlrev_b32_e32 v0, 2, v41
	v_lshl_add_u64 v[2:3], v[2:3], 0, v[0:1]
	global_load_dwordx4 v[8:11], v[2:3], off
	s_cmp_lt_i32 s64, 64
	s_cbranch_scc1 .Lcpf_skip23
	s_lshl_b32 s100, s68, 7
	s_mov_b32 s101, 0
	v_lshl_add_u64 v[70:71], s[100:101], 0, v[2:3]
	global_load_dwordx4 v[66:69], v[70:71], off
